# diff attention main loop: wave LDS offset kept in a scalar register, M0 wait states filled by the flag block's scalar adds instead of s_nop
# baseline (speedup 1.0000x reference)
; __device__ __forceinline__ float max3f(float a, float b, float c) { float r; asm("v_max3_f32 %0, %1, %2, %3" : "=v"(r) : "v"(a), "v"(b), "v"(c)); return r; }
; #define SLOAD(i, k0) do { sr_[i].vs0 = ld8(&Vg[(long)((k0) + sr) * LDP + sc]); sr_[i].vs1 = ld8(&Vg[(long)((k0) + 32 + sr) * LDP + sc]); \
;     sr_[i].ks0 = ld8(&Kg[(long)((k0) + sr) * LDP + sc]); sr_[i].ks1 = ld8(&Kg[(long)((k0) + 32 + sr) * LDP + sc]); } while (0)
; #define SWRITE(off, i) do { *(bf16x8*)(V_lds + (off) + vst0) = sr_[i].vs0;          \
;     *(bf16x8*)(V_lds + (off) + vst1) = sr_[i].vs1; int kc = sc * 2;               \
;     *(bf16x8*)(K_lds + (off) + KSWZ(sr, kc)) = sr_[i].ks0;                       \
;     *(bf16x8*)(K_lds + (off) + KSWZ(32 + sr, kc)) = sr_[i].ks1; } while (0)
; #define SWAIT() asm volatile("s_waitcnt vmcnt(0)" ::: "memory")
; template <bool FIRST> __device__ __forceinline__ void partialSM2(f32x16& p0, f32x16& p1, float& m_ref, f32x16& negm, float& alpha) {
;   float pmax = max3f(p0[0], p0[1], p1[0]), pmb = max3f(p0[2], p0[3], p1[1]);
;   pmax = max3f(pmax, p1[2], p1[3]);
; #pragma unroll
;   for (int r = 4; r < 16; r += 4) { pmax = max3f(pmax, p0[r], p0[r + 1]); pmb = max3f(pmb, p0[r + 2], p0[r + 3]); pmax = max3f(pmax, p1[r], p1[r + 1]); pmb = max3f(pmb, p1[r + 2], p1[r + 3]); }
;   pmax = max3f(pmax, pmb, pmb);
;   { auto rr = __builtin_amdgcn_permlane32_swap(__float_as_uint(pmax), __float_as_uint(pmax), false, false);
;     pmax = fmaxf(__uint_as_float(rr[0]), __uint_as_float(rr[1])); }
;   alpha = 1.f;
;   if (FIRST || !__builtin_expect(__all(pmax <= THR), 1)) {
;     const float dl = FIRST ? pmax : fmaxf(pmax, 0.f); m_ref += dl; if (!FIRST) alpha = __builtin_amdgcn_exp2f(-dl);
; #pragma unroll
;     for (int r = 0; r < 16; ++r) { p0[r] -= dl; p1[r] -= dl; negm[r] -= dl; }
;   }
; template <int MODE, int ORD> ...
;     ...
;   SLOAD(SE, 0); asm volatile("s_waitcnt vmcnt(0)" ::: "memory"); SWRITE(0, SE); __syncthreads();
;   bL = tab[0]; bR = tab[256];
;   SETBE(0); qkt<ND0>(pA0, pA1, K_lds, qr, r32, hi, cboff, negm); BIAS(pA0, pA1, 0); partialSM2<MODE == 0>(pA0, pA1, m_reg, negm, alA);
;   SLOAD(SO, KVBLK);
;   SWAIT(); SWRITE(SLOT, SO); __syncthreads();
;   int op = 0, oc = SLOT, on = 2 * SLOT;
.LBB0_162:
	v_and_b32_e32 v1, 63, v40
	v_lshlrev_b32_e32 v35, 4, v1
	v_lshlrev_b32_e32 v34, 3, v1
	v_and_b32_e32 v35, 0xc0, v35
	v_lshlrev_b32_e32 v36, 1, v1
	v_and_or_b32 v35, v34, 24, v35
	v_and_b32_e32 v36, 32, v36
	v_and_b32_e32 v34, 0x100, v34
	s_cmp_lg_u32 0, -1
	v_or3_b32 v34, v35, v36, v34
	s_cselect_b32 s34, 0, 0
	v_add_u32_e32 v199, s34, v34
	v_max3_f32 v34, v18, v19, v2
	v_max3_f32 v35, v20, v21, v3
	v_cndmask_b32_e64 v214, 0, v46, s[0:1]
	v_max3_f32 v34, v34, v4, v5
	v_max3_f32 v35, v35, v24, v25
	s_and_b32 s0, s63, 0x3fffffc0
	v_max3_f32 v34, v34, v22, v23
	v_max3_f32 v35, v35, v8, v9
	s_lshl_b32 s0, s0, 2
	v_max3_f32 v34, v34, v6, v7
	v_max3_f32 v35, v35, v28, v29
	v_add_u32_e32 v36, 0x60, v38
	v_max3_f32 v34, v34, v26, v27
	s_add_i32 s49, s0, 0
	v_max3_f32 v58, v34, v10, v11
	v_add_u32_e32 v34, 64, v38
	v_max3_f32 v59, v35, v12, v13
	v_mad_i64_i32 v[34:35], s[0:1], v34, s73, 0
	v_mad_i64_i32 v[36:37], s[0:1], v36, s73, 0
	v_or_b32_e32 v34, v34, v41
	v_or_b32_e32 v36, v36, v41
	v_lshlrev_b64 v[50:51], 1, v[34:35]
	v_lshlrev_b64 v[52:53], 1, v[36:37]
	v_lshl_add_u64 v[34:35], s[42:43], 0, v[50:51]
	v_lshl_add_u64 v[46:47], s[42:43], 0, v[52:53]
	v_lshl_add_u64 v[50:51], s[18:19], 0, v[50:51]
	v_lshl_add_u64 v[54:55], s[18:19], 0, v[52:53]
	global_load_dwordx4 v[34:37], v[34:35], off
	s_nop 0
	global_load_dwordx4 v[46:49], v[46:47], off
	s_nop 0
	global_load_dwordx4 v[50:53], v[50:51], off offset:2048
	s_nop 0
	global_load_dwordx4 v[54:57], v[54:55], off offset:2048
	v_max3_f32 v41, v58, v30, v31
	v_max3_f32 v58, v59, v32, v33
	s_add_i32 s68, s68, s79
	v_max3_f32 v41, v41, v14, v15
	v_max3_f32 v58, v58, v16, v17
	v_ashrrev_i32_e32 v39, 31, v38
	v_max3_f32 v41, v41, v58, v58
	v_cmp_gt_u32_e64 s[0:1], 32, v1
	v_mov_b32_e32 v58, v41
	s_nop 1
	v_permlane32_swap_b32_e32 v41, v58
	v_max_f32_e32 v58, v58, v58
	v_max_f32_e32 v41, v41, v41
	v_max_f32_e32 v41, v41, v58
	v_sub_f32_e32 v64, v0, v41
	v_add_u32_e32 v0, s68, v184
	v_sub_f32_e32 v81, v3, v41
	v_sub_f32_e32 v80, v2, v41
	v_sub_u32_e32 v202, v197, v0
	v_lshl_add_u64 v[0:1], s[10:11], 0, v[38:39]
	v_mov_b32_e32 v2, s78
	v_mov_b32_e32 v3, v205
	v_mad_u64_u32 v[2:3], s[10:11], v0, s53, v[2:3]
	v_mov_b32_e32 v0, v3
	v_sub_f32_e32 v18, v18, v41
	v_sub_f32_e32 v19, v19, v41
	v_sub_f32_e32 v20, v20, v41
	v_sub_f32_e32 v21, v21, v41
	v_sub_f32_e32 v22, v22, v41
	v_sub_f32_e32 v23, v23, v41
	v_sub_f32_e32 v24, v24, v41
	v_sub_f32_e32 v25, v25, v41
	v_sub_f32_e32 v26, v26, v41
	v_sub_f32_e32 v27, v27, v41
	v_sub_f32_e32 v28, v28, v41
	v_sub_f32_e32 v29, v29, v41
	v_sub_f32_e32 v30, v30, v41
	v_sub_f32_e32 v31, v31, v41
	v_sub_f32_e32 v32, v32, v41
	v_sub_f32_e32 v33, v33, v41
	v_mad_u64_u32 v[0:1], s[10:11], v1, s53, v[0:1]
	v_exp_f32_e32 v173, v18
	v_exp_f32_e32 v175, v19
	v_exp_f32_e32 v171, v20
	v_exp_f32_e32 v174, v21
	v_exp_f32_e32 v169, v22
	v_exp_f32_e32 v172, v23
	v_exp_f32_e32 v168, v24
	v_exp_f32_e32 v170, v25
	v_exp_f32_e32 v165, v26
	v_exp_f32_e32 v167, v27
	v_exp_f32_e32 v163, v28
	v_exp_f32_e32 v166, v29
	v_exp_f32_e32 v161, v30
	v_exp_f32_e32 v164, v31
	v_exp_f32_e32 v160, v32
	v_exp_f32_e32 v162, v33
	v_and_b32_e32 v1, 15, v40
	v_readlane_b32 s10, v255, 31
	v_sub_f32_e32 v93, v15, v41
	v_sub_f32_e32 v92, v14, v41
	s_waitcnt vmcnt(0)
	v_lshl_or_b32 v2, v1, 4, v2
	v_mov_b32_e32 v3, v0
	v_readlane_b32 s11, v255, 32
	v_mov_b32_e32 v14, v205
	v_mov_b32_e32 v15, v205
	s_add_i32 s49, s49, 0x18000
	v_sub_f32_e32 v95, v17, v41
	v_sub_f32_e32 v94, v16, v41
	v_sub_f32_e32 v91, v13, v41
	v_sub_f32_e32 v90, v12, v41
	v_sub_f32_e32 v89, v11, v41
	v_sub_f32_e32 v88, v10, v41
	v_sub_f32_e32 v87, v9, v41
	v_sub_f32_e32 v86, v8, v41
	v_sub_f32_e32 v85, v7, v41
	v_sub_f32_e32 v84, v6, v41
	v_sub_f32_e32 v83, v5, v41
	v_sub_f32_e32 v82, v4, v41
	s_waitcnt vmcnt(3)
	ds_write_b128 v44, v[34:37] offset:32768
	s_waitcnt vmcnt(2)
	ds_write_b128 v45, v[46:49] offset:32768
	s_waitcnt vmcnt(1)
	ds_write_b128 v42, v[50:53] offset:49152
	s_waitcnt vmcnt(0)
	ds_write_b128 v43, v[54:57] offset:49152
	v_lshl_add_u64 v[176:177], s[10:11], 0, v[2:3]
	v_and_b32_e32 v240, 63, v244
	s_lshl_b32 s100, s62, 2
	s_and_b32 s101, s62, 1
	s_lshl_b32 s101, s101, 3
	v_lshrrev_b32_e32 v241, 4, v240
	v_or_b32_e32 v242, s101, v241
	v_and_b32_e32 v243, 15, v240
	v_xor_b32_e32 v242, v243, v242
	v_add_u32_e32 v245, s100, v241
	v_mul_u32_u24_e32 v245, 0x2400, v245
	v_lshl_add_u32 v234, v242, 4, v245
	v_xor_b32_e32 v242, 4, v242
	v_add_u32_e32 v245, 0x8c00, v245
	v_lshl_add_u32 v235, v242, 4, v245
	v_bfe_u32 v241, v240, 2, 3
	s_lshl_b32 s101, s62, 3
	v_or_b32_e32 v241, s101, v241
	v_mov_b32_e32 v242, v241
	v_subrev_u32_e32 v242, s100, v242
	v_mul_u32_u24_e32 v242, 0x2400, v242
	v_lshrrev_b32_e32 v243, 5, v240
	v_lshlrev_b32_e32 v243, 6, v243
	v_and_b32_e32 v245, 3, v240
	v_lshl_add_u32 v243, v245, 4, v243
	v_add_u32_e32 v236, v242, v243
	v_add_u32_e32 v236, 0x800, v236
	v_subrev_u32_e32 v237, 0x380, v236
	v_readfirstlane_b32 s100, v176
	v_readfirstlane_b32 s101, v177
	s_lshl_b32 s79, s62, 11
	v_mov_b32_e32 v0, v205
	v_mov_b32_e32 v1, v205
	v_mov_b32_e32 v2, v205
	v_mov_b32_e32 v3, v205
	v_mov_b32_e32 v4, v205
	v_mov_b32_e32 v5, v205
	v_mov_b32_e32 v6, v205
	v_mov_b32_e32 v7, v205
	v_mov_b32_e32 v8, v205
	v_mov_b32_e32 v9, v205
	v_mov_b32_e32 v10, v205
	v_mov_b32_e32 v11, v205
	v_mov_b32_e32 v12, v205
	v_mov_b32_e32 v13, v205
	v_mov_b64_e32 v[62:63], v[14:15]
	v_mov_b64_e32 v[46:47], v[14:15]
	v_mov_b64_e32 v[30:31], v[14:15]
	s_mov_b32 s56, 0
	s_mov_b32 s57, 2
	v_mov_b32_e32 v65, v64
	v_mov_b32_e32 v66, v64
	v_mov_b32_e32 v67, v64
	v_mov_b32_e32 v68, v64
	v_mov_b32_e32 v69, v64
	v_mov_b32_e32 v70, v64
	v_mov_b32_e32 v71, v64
	v_mov_b32_e32 v72, v64
	v_mov_b32_e32 v73, v64
	v_mov_b32_e32 v74, v64
	v_mov_b32_e32 v75, v64
	v_mov_b32_e32 v76, v64
	v_mov_b32_e32 v77, v64
	v_mov_b32_e32 v78, v64
	v_mov_b32_e32 v79, v64
	s_add_i32 s19, s92, 0x9f
	v_lshl_add_u32 v186, v184, 2, s49
	s_sub_i32 s42, 0, s68
	v_mov_b32_e32 v187, 0
	v_mov_b32_e32 v203, 1.0
	s_mov_b32 s18, 0x10000
	s_mov_b32 s43, 0x8000
	v_mov_b64_e32 v[60:61], v[12:13]
	v_mov_b64_e32 v[58:59], v[10:11]
	v_mov_b64_e32 v[56:57], v[8:9]
	v_mov_b64_e32 v[54:55], v[6:7]
	v_mov_b64_e32 v[52:53], v[4:5]
	v_mov_b64_e32 v[50:51], v[2:3]
	v_mov_b64_e32 v[48:49], v[0:1]
	v_mov_b64_e32 v[44:45], v[12:13]
	v_mov_b64_e32 v[42:43], v[10:11]
	v_mov_b64_e32 v[40:41], v[8:9]
	v_mov_b64_e32 v[38:39], v[6:7]
	v_mov_b64_e32 v[36:37], v[4:5]
	v_mov_b64_e32 v[34:35], v[2:3]
	v_mov_b64_e32 v[32:33], v[0:1]
	v_mov_b64_e32 v[28:29], v[12:13]
	v_mov_b64_e32 v[26:27], v[10:11]
	v_mov_b64_e32 v[24:25], v[8:9]
	v_mov_b64_e32 v[22:23], v[6:7]
	v_mov_b64_e32 v[20:21], v[4:5]
	v_mov_b64_e32 v[18:19], v[2:3]
	v_mov_b64_e32 v[16:17], v[0:1]
	s_mov_b32 s10, 0
	s_waitcnt lgkmcnt(0)
	s_barrier
.LBB0_163:
	s_mov_b32 s68, s43
	s_mov_b32 s43, s10
	s_add_i32 m0, s79, s18
	s_add_i32 s78, s42, s56
	global_load_lds_dwordx4 v236, s[100:101]
	global_load_lds_dwordx4 v237, s[100:101] offset:1024
	s_addk_i32 m0, 0x4000
	s_add_i32 s34, s56, 64
	global_load_lds_dwordx4 v234, s[100:101]
	global_load_lds_dwordx4 v235, s[100:101] offset:1024
	s_add_u32 s100, s100, 0x90000
	s_addc_u32 s101, s101, 0
	s_add_i32 s35, s78, 0x7f
	s_cmpk_gt_i32 s35, 0xff80
	s_cselect_b64 s[10:11], -1, 0
	s_cmp_lt_u32 s34, s19
	s_cselect_b64 s[80:81], -1, 0
	s_and_b64 s[10:11], s[10:11], s[80:81]
	s_cmpk_lt_i32 s35, 0xff81
	s_cselect_b64 vcc, -1, 0
	v_cndmask_b32_e32 v96, v200, v195, vcc
	v_cndmask_b32_e64 v215, v96, 0, s[10:11]
	v_cmp_eq_f32_e32 vcc, v215, v214
	s_cbranch_vccnz .LBB0_165
	v_sub_f32_e32 v96, v215, v214
	v_pk_add_f32 v[78:79], v[78:79], v[96:97] op_sel_hi:[1,0]
	v_pk_add_f32 v[76:77], v[76:77], v[96:97] op_sel_hi:[1,0]
	v_pk_add_f32 v[74:75], v[74:75], v[96:97] op_sel_hi:[1,0]
	v_pk_add_f32 v[72:73], v[72:73], v[96:97] op_sel_hi:[1,0]
	v_pk_add_f32 v[70:71], v[70:71], v[96:97] op_sel_hi:[1,0]
	v_pk_add_f32 v[68:69], v[68:69], v[96:97] op_sel_hi:[1,0]
	v_pk_add_f32 v[66:67], v[66:67], v[96:97] op_sel_hi:[1,0]
	v_pk_add_f32 v[64:65], v[64:65], v[96:97] op_sel_hi:[1,0]
	s_branch .LBB0_166

.LBB0_174:
	s_addk_i32 s56, 0x80
	s_waitcnt vmcnt(0) lgkmcnt(0)
	s_barrier
	s_add_i32 m0, s79, s43
	s_addk_i32 s78, 0xbf
	global_load_lds_dwordx4 v236, s[100:101]
	global_load_lds_dwordx4 v237, s[100:101] offset:1024
	s_addk_i32 m0, 0x4000
	s_nop 0
	global_load_lds_dwordx4 v234, s[100:101]
	global_load_lds_dwordx4 v235, s[100:101] offset:1024
	s_add_u32 s100, s100, 0x90000
	s_addc_u32 s101, s101, 0
	s_cmpk_gt_i32 s78, 0xff80
	s_cselect_b64 s[10:11], -1, 0
	s_cmp_lt_u32 s56, s19
	s_cselect_b64 s[80:81], -1, 0
	s_and_b64 s[10:11], s[10:11], s[80:81]
	s_cmpk_lt_i32 s78, 0xff81
	s_cselect_b64 vcc, -1, 0
	v_cndmask_b32_e32 v80, v200, v195, vcc
	v_cndmask_b32_e64 v214, v80, 0, s[10:11]
	v_cmp_eq_f32_e32 vcc, v214, v215
	s_cbranch_vccnz .LBB0_176
	v_sub_f32_e32 v80, v214, v215
	v_pk_add_f32 v[78:79], v[80:81], v[78:79] op_sel_hi:[0,1]
	v_pk_add_f32 v[76:77], v[80:81], v[76:77] op_sel_hi:[0,1]
	v_pk_add_f32 v[74:75], v[80:81], v[74:75] op_sel_hi:[0,1]
	v_pk_add_f32 v[72:73], v[80:81], v[72:73] op_sel_hi:[0,1]
	v_pk_add_f32 v[70:71], v[80:81], v[70:71] op_sel_hi:[0,1]
	v_pk_add_f32 v[68:69], v[80:81], v[68:69] op_sel_hi:[0,1]
	v_pk_add_f32 v[66:67], v[80:81], v[66:67] op_sel_hi:[0,1]
	v_pk_add_f32 v[64:65], v[80:81], v[64:65] op_sel_hi:[0,1]
	s_branch .LBB0_177
